# P10-conv-gelu-epilogue-regular-blocks-hand-rewritten-dpp-fmac-and-weight-prefetch
# speedup vs baseline: 1.0119x; 1.0063x over previous
; #define GAS __attribute__((address_space(1)))
; #define LAS __attribute__((address_space(3)))
;     template <bool SAMPLE> __device__ __forceinline__ void body(const pg8::f32x4 (&acc)[2][2][4][2], const pg8::Unit& u, int wr, int fr, int cl0_, int acol0, LAS float* CW, LAS float* BD, LAS float* RSL) const {
;     ...
;                 const int fro = pg8_opq(fr), cl0 = pg8_opq(cl0_);
;                 const int rl = ai * 128 + wr * 64 + m * 16 + fro, row = u.pm * 256 + rl; const float rs = RSL[rl];
;                 v4u hw;
; #pragma unroll
;                 for (int n = 0; n < 2; ++n) {
;                     f32x4 cv2[2];
; #pragma unroll
;                     for (int bj = 0; bj < 2; ++bj) {
;                         const int cl = bj * 128 + cl0 + 4 * n, gcol = bj * DFF + acol0 + cl0 + 4 * n; const f32x4 x = acc[ai][bj][m][n] * rs;
;                         f32x4 s1, s2;
; #pragma unroll
;                         for (int i = 0; i < 4; ++i) { s1[i] = dpp_ror1(x[i]); s2[i] = dpp_ror2(x[i]); }
;                         if (SAMPLE) { const int t = fro & 3; const float* sp = state_conv + (size_t)((row - MP) >> 2) * 2 * UPW + gcol;
;                             const f32x4 S0 = *(const GAS f32x4*)sp, S1 = *(const GAS f32x4*)(sp + UPW);
; #pragma unroll
;                             for (int i = 0; i < 4; ++i) { s1[i] = (t >= 1) ? s1[i] : S1[i]; s2[i] = (t >= 2) ? s2[i] : (t == 1 ? S1[i] : S0[i]); }
;                             if (t >= 2) *(GAS f32x4*)(out + O_CVS + ((size_t)((row - MP) >> 2) * 2 + (t - 2)) * UPW + gcol) = x;
;                         } else if (m > 0) { const f32x4 xp = acc[ai][bj][m > 0 ? m - 1 : 0][n] * RSL[rl - 16];
; #pragma unroll
;                             for (int i = 0; i < 4; ++i) { s1[i] = dpp_ror1(fro == 15 ? xp[i] : x[i]); s2[i] = dpp_ror2(fro >= 14 ? xp[i] : x[i]); }
;                         } else { const int pb = (wr == 1) ? ai * 2 : 1;
;                             const int pr0 = (pb >> 1) * 128 + (pb & 1) * 64 + 62;
;                             const f32x4 b2 = *(const LAS f32x4*)(BD + (pb * 2 + 0) * 256 + cl) * RSL[pr0], b1 = *(const LAS f32x4*)(BD + (pb * 2 + 1) * 256 + cl) * RSL[pr0 + 1];
; #pragma unroll
;                             for (int i = 0; i < 4; ++i) { s1[i] = (fro >= 1) ? s1[i] : b1[i]; s2[i] = (fro >= 2) ? s2[i] : (fro == 1 ? b1[i] : b2[i]); }
;                         }
.LBB0_2606:
	s_or_b64 exec, exec, s[0:1]
	v_readlane_b32 s0, v255, 23
	v_mov_b32_e32 v140, v198
	v_lshl_add_u32 v141, v198, 2, 0
	v_cmp_eq_u32_e64 s[4:5], 15, v199
	v_cmp_lt_i32_e64 s[2:3], 13, v199
	v_add_u32_e32 v158, s0, v199
	v_add_u32_e32 v141, 0x20000, v141
	v_lshl_add_u32 v159, v158, 2, 0
	v_add_u32_e32 v159, 0x22fc0, v159
	ds_read_b32 v138, v159 offset:64
	ds_read_b32 v168, v159
	ds_read_b128 v[204:207], v141
	ds_read_b128 v[208:211], v141 offset:1024
	ds_read_b128 v[212:215], v141 offset:2048
	ds_read_b128 v[216:219], v141 offset:3072
	ds_read_b128 v[228:231], v141 offset:512
	ds_read_b128 v[232:235], v141 offset:1536
	ds_read_b128 v[236:239], v141 offset:2560
	ds_read_b128 v[240:243], v141 offset:3584
	v_cmp_lt_i32_e32 vcc, 1, v158
	ds_read_b128 v[244:247], v141 offset:16
	ds_read_b128 v[248:251], v141 offset:1040
	ds_read_b128 v[142:145], v141 offset:2064
	ds_read_b128 v[146:149], v141 offset:3088
	s_waitcnt lgkmcnt(8)
	v_pk_mul_f32 v[134:135], v[110:111], v[138:139] op_sel_hi:[1,0]
	v_pk_mul_f32 v[136:137], v[112:113], v[138:139] op_sel_hi:[1,0]
	v_pk_mul_f32 v[150:151], v[126:127], v[168:169] op_sel_hi:[1,0]
	v_pk_mul_f32 v[152:153], v[128:129], v[168:169] op_sel_hi:[1,0]
	v_cndmask_b32_e64 v154, v134, v150, s[4:5]
	v_cndmask_b32_e64 v155, v135, v151, s[4:5]
	v_cndmask_b32_e64 v156, v136, v152, s[4:5]
	v_cndmask_b32_e64 v157, v137, v153, s[4:5]
	v_cndmask_b32_e64 v150, v134, v150, s[2:3]
	v_cndmask_b32_e64 v151, v135, v151, s[2:3]
	v_cndmask_b32_e64 v152, v136, v152, s[2:3]
	v_cndmask_b32_e64 v153, v137, v153, s[2:3]
	v_fmac_f32_dpp v216, v150, v204 row_ror:2 row_mask:0xf bank_mask:0xf
	v_fmac_f32_dpp v217, v151, v205 row_ror:2 row_mask:0xf bank_mask:0xf
	v_fmac_f32_dpp v218, v152, v206 row_ror:2 row_mask:0xf bank_mask:0xf
	v_fmac_f32_dpp v219, v153, v207 row_ror:2 row_mask:0xf bank_mask:0xf
	v_fmac_f32_dpp v216, v154, v208 row_ror:1 row_mask:0xf bank_mask:0xf
	v_fmac_f32_dpp v217, v155, v209 row_ror:1 row_mask:0xf bank_mask:0xf
	v_fmac_f32_dpp v218, v156, v210 row_ror:1 row_mask:0xf bank_mask:0xf
	v_fmac_f32_dpp v219, v157, v211 row_ror:1 row_mask:0xf bank_mask:0xf
	v_pk_fma_f32 v[160:161], v[134:135], v[212:213], v[216:217]
	v_pk_fma_f32 v[162:163], v[136:137], v[214:215], v[218:219]
	ds_read_b128 v[204:207], v141 offset:528
	ds_read_b128 v[208:211], v141 offset:1552
	ds_read_b128 v[212:215], v141 offset:2576
	ds_read_b128 v[216:219], v141 offset:3600
	s_waitcnt lgkmcnt(8)
	v_pk_mul_f32 v[134:135], v[106:107], v[138:139] op_sel_hi:[1,0]
	v_pk_mul_f32 v[136:137], v[108:109], v[138:139] op_sel_hi:[1,0]
	v_pk_mul_f32 v[150:151], v[122:123], v[168:169] op_sel_hi:[1,0]
	v_pk_mul_f32 v[152:153], v[124:125], v[168:169] op_sel_hi:[1,0]
	v_cndmask_b32_e64 v154, v134, v150, s[4:5]
	v_cndmask_b32_e64 v155, v135, v151, s[4:5]
	v_cndmask_b32_e64 v156, v136, v152, s[4:5]
	v_cndmask_b32_e64 v157, v137, v153, s[4:5]
	v_cndmask_b32_e64 v150, v134, v150, s[2:3]
	v_cndmask_b32_e64 v151, v135, v151, s[2:3]
	v_cndmask_b32_e64 v152, v136, v152, s[2:3]
	v_cndmask_b32_e64 v153, v137, v153, s[2:3]
	v_fmac_f32_dpp v240, v150, v228 row_ror:2 row_mask:0xf bank_mask:0xf
	v_fmac_f32_dpp v241, v151, v229 row_ror:2 row_mask:0xf bank_mask:0xf
	v_fmac_f32_dpp v242, v152, v230 row_ror:2 row_mask:0xf bank_mask:0xf
	v_fmac_f32_dpp v243, v153, v231 row_ror:2 row_mask:0xf bank_mask:0xf
	v_fmac_f32_dpp v240, v154, v232 row_ror:1 row_mask:0xf bank_mask:0xf
	v_fmac_f32_dpp v241, v155, v233 row_ror:1 row_mask:0xf bank_mask:0xf
	v_fmac_f32_dpp v242, v156, v234 row_ror:1 row_mask:0xf bank_mask:0xf
	v_fmac_f32_dpp v243, v157, v235 row_ror:1 row_mask:0xf bank_mask:0xf
	v_pk_fma_f32 v[164:165], v[134:135], v[236:237], v[240:241]
	v_pk_fma_f32 v[166:167], v[136:137], v[238:239], v[242:243]
	v_pk_mul_f32 v[134:135], v[160:161], v[160:161]
	v_pk_mul_f32 v[136:137], v[162:163], v[162:163]
	v_pk_fma_f32 v[134:135], v[134:135], s[54:55], 1.0 op_sel_hi:[1,0,0]
	v_pk_mul_f32 v[150:151], v[160:161], s[56:57] op_sel_hi:[1,0]
	v_pk_fma_f32 v[136:137], v[136:137], s[54:55], 1.0 op_sel_hi:[1,0,0]
	v_pk_mul_f32 v[152:153], v[162:163], s[56:57] op_sel_hi:[1,0]
	v_pk_mul_f32 v[134:135], v[150:151], v[134:135]
	v_pk_mul_f32 v[136:137], v[152:153], v[136:137]
	v_pk_mul_f32 v[134:135], v[134:135], s[58:59] op_sel_hi:[1,0]
	v_pk_mul_f32 v[136:137], v[136:137], s[58:59] op_sel_hi:[1,0]
	v_exp_f32_e32 v134, v134
	v_exp_f32_e32 v135, v135
	v_exp_f32_e32 v136, v136
	v_exp_f32_e32 v137, v137
	v_pk_add_f32 v[134:135], v[134:135], 1.0 op_sel_hi:[1,0]
	s_nop 0
	v_pk_add_f32 v[136:137], v[136:137], 1.0 op_sel_hi:[1,0]
	v_rcp_f32_e32 v134, v134
	v_rcp_f32_e32 v135, v135
	v_rcp_f32_e32 v136, v136
	v_rcp_f32_e32 v137, v137
	v_pk_mul_f32 v[134:135], v[160:161], v[134:135]
	v_pk_mul_f32 v[136:137], v[162:163], v[136:137]
	v_pk_mul_f32 v[134:135], v[164:165], v[134:135]
	v_pk_mul_f32 v[136:137], v[166:167], v[136:137]
	s_nop 0
	v_cvt_pk_bf16_f32 v130, v134, v135
	v_cvt_pk_bf16_f32 v131, v136, v137
	s_waitcnt lgkmcnt(4)
	v_pk_mul_f32 v[134:135], v[102:103], v[138:139] op_sel_hi:[1,0]
	v_pk_mul_f32 v[136:137], v[104:105], v[138:139] op_sel_hi:[1,0]
	v_pk_mul_f32 v[150:151], v[118:119], v[168:169] op_sel_hi:[1,0]
	v_pk_mul_f32 v[152:153], v[120:121], v[168:169] op_sel_hi:[1,0]
	v_cndmask_b32_e64 v154, v134, v150, s[4:5]
	v_cndmask_b32_e64 v155, v135, v151, s[4:5]
	v_cndmask_b32_e64 v156, v136, v152, s[4:5]
	v_cndmask_b32_e64 v157, v137, v153, s[4:5]
	v_cndmask_b32_e64 v150, v134, v150, s[2:3]
	v_cndmask_b32_e64 v151, v135, v151, s[2:3]
	v_cndmask_b32_e64 v152, v136, v152, s[2:3]
	v_cndmask_b32_e64 v153, v137, v153, s[2:3]
	v_fmac_f32_dpp v146, v150, v244 row_ror:2 row_mask:0xf bank_mask:0xf
	v_fmac_f32_dpp v147, v151, v245 row_ror:2 row_mask:0xf bank_mask:0xf
	v_fmac_f32_dpp v148, v152, v246 row_ror:2 row_mask:0xf bank_mask:0xf
	v_fmac_f32_dpp v149, v153, v247 row_ror:2 row_mask:0xf bank_mask:0xf
	v_fmac_f32_dpp v146, v154, v248 row_ror:1 row_mask:0xf bank_mask:0xf
	v_fmac_f32_dpp v147, v155, v249 row_ror:1 row_mask:0xf bank_mask:0xf
	v_fmac_f32_dpp v148, v156, v250 row_ror:1 row_mask:0xf bank_mask:0xf
	v_fmac_f32_dpp v149, v157, v251 row_ror:1 row_mask:0xf bank_mask:0xf
	v_pk_fma_f32 v[160:161], v[134:135], v[142:143], v[146:147]
	v_pk_fma_f32 v[162:163], v[136:137], v[144:145], v[148:149]
	s_waitcnt lgkmcnt(0)
; #define GAS __attribute__((address_space(1)))
; #define LAS __attribute__((address_space(3)))
;     template <bool SAMPLE> __device__ __forceinline__ void body(const pg8::f32x4 (&acc)[2][2][4][2], const pg8::Unit& u, int wr, int fr, int cl0_, int acol0, LAS float* CW, LAS float* BD, LAS float* RSL) const {
;     ...
;                 const int fro = pg8_opq(fr), cl0 = pg8_opq(cl0_);
;                 const int rl = ai * 128 + wr * 64 + m * 16 + fro, row = u.pm * 256 + rl; const float rs = RSL[rl];
;                 v4u hw;
; #pragma unroll
;                 for (int n = 0; n < 2; ++n) {
;                     f32x4 cv2[2];
; #pragma unroll
;                     for (int bj = 0; bj < 2; ++bj) {
;                         const int cl = bj * 128 + cl0 + 4 * n, gcol = bj * DFF + acol0 + cl0 + 4 * n; const f32x4 x = acc[ai][bj][m][n] * rs;
;                         f32x4 s1, s2;
; #pragma unroll
;                         for (int i = 0; i < 4; ++i) { s1[i] = dpp_ror1(x[i]); s2[i] = dpp_ror2(x[i]); }
;                         if (SAMPLE) { const int t = fro & 3; const float* sp = state_conv + (size_t)((row - MP) >> 2) * 2 * UPW + gcol;
;                             const f32x4 S0 = *(const GAS f32x4*)sp, S1 = *(const GAS f32x4*)(sp + UPW);
; #pragma unroll
;                             for (int i = 0; i < 4; ++i) { s1[i] = (t >= 1) ? s1[i] : S1[i]; s2[i] = (t >= 2) ? s2[i] : (t == 1 ? S1[i] : S0[i]); }
;                             if (t >= 2) *(GAS f32x4*)(out + O_CVS + ((size_t)((row - MP) >> 2) * 2 + (t - 2)) * UPW + gcol) = x;
;                         } else if (m > 0) { const f32x4 xp = acc[ai][bj][m > 0 ? m - 1 : 0][n] * RSL[rl - 16];
; #pragma unroll
;                             for (int i = 0; i < 4; ++i) { s1[i] = dpp_ror1(fro == 15 ? xp[i] : x[i]); s2[i] = dpp_ror2(fro >= 14 ? xp[i] : x[i]); }
;                         } else { const int pb = (wr == 1) ? ai * 2 : 1;
;                             const int pr0 = (pb >> 1) * 128 + (pb & 1) * 64 + 62;
;                             const f32x4 b2 = *(const LAS f32x4*)(BD + (pb * 2 + 0) * 256 + cl) * RSL[pr0], b1 = *(const LAS f32x4*)(BD + (pb * 2 + 1) * 256 + cl) * RSL[pr0 + 1];
; #pragma unroll
;                             for (int i = 0; i < 4; ++i) { s1[i] = (fro >= 1) ? s1[i] : b1[i]; s2[i] = (fro >= 2) ? s2[i] : (fro == 1 ? b1[i] : b2[i]); }
;                         }
	v_pk_mul_f32 v[134:135], v[98:99], v[138:139] op_sel_hi:[1,0]
	v_pk_mul_f32 v[136:137], v[100:101], v[138:139] op_sel_hi:[1,0]
	v_pk_mul_f32 v[150:151], v[114:115], v[168:169] op_sel_hi:[1,0]
	v_pk_mul_f32 v[152:153], v[116:117], v[168:169] op_sel_hi:[1,0]
	v_cndmask_b32_e64 v154, v134, v150, s[4:5]
	v_cndmask_b32_e64 v155, v135, v151, s[4:5]
	v_cndmask_b32_e64 v156, v136, v152, s[4:5]
	v_cndmask_b32_e64 v157, v137, v153, s[4:5]
	v_cndmask_b32_e64 v150, v134, v150, s[2:3]
	v_cndmask_b32_e64 v151, v135, v151, s[2:3]
	v_cndmask_b32_e64 v152, v136, v152, s[2:3]
	v_cndmask_b32_e64 v153, v137, v153, s[2:3]
	v_fmac_f32_dpp v216, v150, v204 row_ror:2 row_mask:0xf bank_mask:0xf
	v_fmac_f32_dpp v217, v151, v205 row_ror:2 row_mask:0xf bank_mask:0xf
	v_fmac_f32_dpp v218, v152, v206 row_ror:2 row_mask:0xf bank_mask:0xf
	v_fmac_f32_dpp v219, v153, v207 row_ror:2 row_mask:0xf bank_mask:0xf
	v_fmac_f32_dpp v216, v154, v208 row_ror:1 row_mask:0xf bank_mask:0xf
	v_fmac_f32_dpp v217, v155, v209 row_ror:1 row_mask:0xf bank_mask:0xf
	v_fmac_f32_dpp v218, v156, v210 row_ror:1 row_mask:0xf bank_mask:0xf
	v_fmac_f32_dpp v219, v157, v211 row_ror:1 row_mask:0xf bank_mask:0xf
	v_pk_fma_f32 v[164:165], v[134:135], v[212:213], v[216:217]
	v_pk_fma_f32 v[166:167], v[136:137], v[214:215], v[218:219]
	v_pk_mul_f32 v[134:135], v[160:161], v[160:161]
	v_pk_mul_f32 v[136:137], v[162:163], v[162:163]
	v_pk_fma_f32 v[134:135], v[134:135], s[54:55], 1.0 op_sel_hi:[1,0,0]
	v_pk_mul_f32 v[150:151], v[160:161], s[56:57] op_sel_hi:[1,0]
	v_pk_fma_f32 v[136:137], v[136:137], s[54:55], 1.0 op_sel_hi:[1,0,0]
	v_pk_mul_f32 v[152:153], v[162:163], s[56:57] op_sel_hi:[1,0]
	v_pk_mul_f32 v[134:135], v[150:151], v[134:135]
	v_pk_mul_f32 v[136:137], v[152:153], v[136:137]
	v_pk_mul_f32 v[134:135], v[134:135], s[58:59] op_sel_hi:[1,0]
	v_pk_mul_f32 v[136:137], v[136:137], s[58:59] op_sel_hi:[1,0]
	v_exp_f32_e32 v134, v134
	v_exp_f32_e32 v135, v135
	v_exp_f32_e32 v136, v136
	v_exp_f32_e32 v137, v137
	v_pk_add_f32 v[134:135], v[134:135], 1.0 op_sel_hi:[1,0]
	s_nop 0
	v_pk_add_f32 v[136:137], v[136:137], 1.0 op_sel_hi:[1,0]
	v_rcp_f32_e32 v134, v134
	v_rcp_f32_e32 v135, v135
	v_rcp_f32_e32 v136, v136
	v_rcp_f32_e32 v137, v137
	v_pk_mul_f32 v[134:135], v[160:161], v[134:135]
	v_pk_mul_f32 v[136:137], v[162:163], v[136:137]
	v_pk_mul_f32 v[134:135], v[164:165], v[134:135]
	v_pk_mul_f32 v[136:137], v[166:167], v[136:137]
	s_nop 0
	v_cvt_pk_bf16_f32 v132, v134, v135
	v_cvt_pk_bf16_f32 v133, v136, v137
	s_and_saveexec_b64 s[0:1], vcc
	s_cbranch_execz .LBB0_2608
	v_add_u32_e32 v136, s16, v158
	v_mov_b64_e32 v[134:135], s[50:51]
	v_mad_i64_i32 v[134:135], s[2:3], v136, s82, v[134:135]
	v_ashrrev_i32_e32 v141, 31, v140
	v_lshl_add_u64 v[134:135], s[36:37], 1, v[134:135]
	v_lshl_add_u64 v[134:135], v[140:141], 1, v[134:135]
	global_store_dwordx4 v[134:135], v[130:133], off
.LBB0_2608:
	s_or_b64 exec, exec, s[0:1]
	v_readlane_b32 s0, v255, 15
	v_mov_b32_e32 v140, v198
	v_lshl_add_u32 v141, v198, 2, 0
	v_cmp_eq_u32_e64 s[4:5], 15, v199
	v_cmp_lt_i32_e64 s[2:3], 13, v199
	v_add_u32_e32 v158, s0, v199
	v_add_u32_e32 v141, 0x20000, v141
	v_lshl_add_u32 v159, v158, 2, 0
	v_add_u32_e32 v159, 0x22fc0, v159
	ds_read_b32 v138, v159 offset:64
	ds_read_b32 v168, v159
	ds_read_b128 v[204:207], v141
	ds_read_b128 v[208:211], v141 offset:1024
	ds_read_b128 v[212:215], v141 offset:2048
	ds_read_b128 v[216:219], v141 offset:3072
	ds_read_b128 v[228:231], v141 offset:512
	ds_read_b128 v[232:235], v141 offset:1536
	ds_read_b128 v[236:239], v141 offset:2560
	ds_read_b128 v[240:243], v141 offset:3584
	v_cmp_lt_i32_e32 vcc, 1, v158
	ds_read_b128 v[244:247], v141 offset:16
	ds_read_b128 v[248:251], v141 offset:1040
	ds_read_b128 v[142:145], v141 offset:2064
	ds_read_b128 v[146:149], v141 offset:3088
	s_waitcnt lgkmcnt(8)
	v_pk_mul_f32 v[134:135], v[94:95], v[138:139] op_sel_hi:[1,0]
	v_pk_mul_f32 v[136:137], v[96:97], v[138:139] op_sel_hi:[1,0]
	v_pk_mul_f32 v[150:151], v[110:111], v[168:169] op_sel_hi:[1,0]
	v_pk_mul_f32 v[152:153], v[112:113], v[168:169] op_sel_hi:[1,0]
	v_cndmask_b32_e64 v154, v134, v150, s[4:5]
	v_cndmask_b32_e64 v155, v135, v151, s[4:5]
	v_cndmask_b32_e64 v156, v136, v152, s[4:5]
	v_cndmask_b32_e64 v157, v137, v153, s[4:5]
	v_cndmask_b32_e64 v150, v134, v150, s[2:3]
	v_cndmask_b32_e64 v151, v135, v151, s[2:3]
	v_cndmask_b32_e64 v152, v136, v152, s[2:3]
	v_cndmask_b32_e64 v153, v137, v153, s[2:3]
	v_fmac_f32_dpp v216, v150, v204 row_ror:2 row_mask:0xf bank_mask:0xf
	v_fmac_f32_dpp v217, v151, v205 row_ror:2 row_mask:0xf bank_mask:0xf
	v_fmac_f32_dpp v218, v152, v206 row_ror:2 row_mask:0xf bank_mask:0xf
	v_fmac_f32_dpp v219, v153, v207 row_ror:2 row_mask:0xf bank_mask:0xf
	v_fmac_f32_dpp v216, v154, v208 row_ror:1 row_mask:0xf bank_mask:0xf
	v_fmac_f32_dpp v217, v155, v209 row_ror:1 row_mask:0xf bank_mask:0xf
	v_fmac_f32_dpp v218, v156, v210 row_ror:1 row_mask:0xf bank_mask:0xf
	v_fmac_f32_dpp v219, v157, v211 row_ror:1 row_mask:0xf bank_mask:0xf
	v_pk_fma_f32 v[160:161], v[134:135], v[212:213], v[216:217]
	v_pk_fma_f32 v[162:163], v[136:137], v[214:215], v[218:219]
	ds_read_b128 v[204:207], v141 offset:528
	ds_read_b128 v[208:211], v141 offset:1552
	ds_read_b128 v[212:215], v141 offset:2576
	ds_read_b128 v[216:219], v141 offset:3600
	s_waitcnt lgkmcnt(8)
; #define GAS __attribute__((address_space(1)))
; #define LAS __attribute__((address_space(3)))
;     template <bool SAMPLE> __device__ __forceinline__ void body(const pg8::f32x4 (&acc)[2][2][4][2], const pg8::Unit& u, int wr, int fr, int cl0_, int acol0, LAS float* CW, LAS float* BD, LAS float* RSL) const {
;     ...
;                 const int fro = pg8_opq(fr), cl0 = pg8_opq(cl0_);
;                 const int rl = ai * 128 + wr * 64 + m * 16 + fro, row = u.pm * 256 + rl; const float rs = RSL[rl];
;                 v4u hw;
; #pragma unroll
;                 for (int n = 0; n < 2; ++n) {
;                     f32x4 cv2[2];
; #pragma unroll
;                     for (int bj = 0; bj < 2; ++bj) {
;                         const int cl = bj * 128 + cl0 + 4 * n, gcol = bj * DFF + acol0 + cl0 + 4 * n; const f32x4 x = acc[ai][bj][m][n] * rs;
;                         f32x4 s1, s2;
; #pragma unroll
;                         for (int i = 0; i < 4; ++i) { s1[i] = dpp_ror1(x[i]); s2[i] = dpp_ror2(x[i]); }
;                         if (SAMPLE) { const int t = fro & 3; const float* sp = state_conv + (size_t)((row - MP) >> 2) * 2 * UPW + gcol;
;                             const f32x4 S0 = *(const GAS f32x4*)sp, S1 = *(const GAS f32x4*)(sp + UPW);
; #pragma unroll
;                             for (int i = 0; i < 4; ++i) { s1[i] = (t >= 1) ? s1[i] : S1[i]; s2[i] = (t >= 2) ? s2[i] : (t == 1 ? S1[i] : S0[i]); }
;                             if (t >= 2) *(GAS f32x4*)(out + O_CVS + ((size_t)((row - MP) >> 2) * 2 + (t - 2)) * UPW + gcol) = x;
;                         } else if (m > 0) { const f32x4 xp = acc[ai][bj][m > 0 ? m - 1 : 0][n] * RSL[rl - 16];
; #pragma unroll
;                             for (int i = 0; i < 4; ++i) { s1[i] = dpp_ror1(fro == 15 ? xp[i] : x[i]); s2[i] = dpp_ror2(fro >= 14 ? xp[i] : x[i]); }
;                         } else { const int pb = (wr == 1) ? ai * 2 : 1;
;                             const int pr0 = (pb >> 1) * 128 + (pb & 1) * 64 + 62;
;                             const f32x4 b2 = *(const LAS f32x4*)(BD + (pb * 2 + 0) * 256 + cl) * RSL[pr0], b1 = *(const LAS f32x4*)(BD + (pb * 2 + 1) * 256 + cl) * RSL[pr0 + 1];
; #pragma unroll
;                             for (int i = 0; i < 4; ++i) { s1[i] = (fro >= 1) ? s1[i] : b1[i]; s2[i] = (fro >= 2) ? s2[i] : (fro == 1 ? b1[i] : b2[i]); }
;                         }
	v_pk_mul_f32 v[134:135], v[90:91], v[138:139] op_sel_hi:[1,0]
	v_pk_mul_f32 v[136:137], v[92:93], v[138:139] op_sel_hi:[1,0]
	v_pk_mul_f32 v[150:151], v[106:107], v[168:169] op_sel_hi:[1,0]
	v_pk_mul_f32 v[152:153], v[108:109], v[168:169] op_sel_hi:[1,0]
	v_cndmask_b32_e64 v154, v134, v150, s[4:5]
	v_cndmask_b32_e64 v155, v135, v151, s[4:5]
	v_cndmask_b32_e64 v156, v136, v152, s[4:5]
	v_cndmask_b32_e64 v157, v137, v153, s[4:5]
	v_cndmask_b32_e64 v150, v134, v150, s[2:3]
	v_cndmask_b32_e64 v151, v135, v151, s[2:3]
	v_cndmask_b32_e64 v152, v136, v152, s[2:3]
	v_cndmask_b32_e64 v153, v137, v153, s[2:3]
	v_fmac_f32_dpp v240, v150, v228 row_ror:2 row_mask:0xf bank_mask:0xf
	v_fmac_f32_dpp v241, v151, v229 row_ror:2 row_mask:0xf bank_mask:0xf
	v_fmac_f32_dpp v242, v152, v230 row_ror:2 row_mask:0xf bank_mask:0xf
	v_fmac_f32_dpp v243, v153, v231 row_ror:2 row_mask:0xf bank_mask:0xf
	v_fmac_f32_dpp v240, v154, v232 row_ror:1 row_mask:0xf bank_mask:0xf
	v_fmac_f32_dpp v241, v155, v233 row_ror:1 row_mask:0xf bank_mask:0xf
	v_fmac_f32_dpp v242, v156, v234 row_ror:1 row_mask:0xf bank_mask:0xf
	v_fmac_f32_dpp v243, v157, v235 row_ror:1 row_mask:0xf bank_mask:0xf
	v_pk_fma_f32 v[164:165], v[134:135], v[236:237], v[240:241]
	v_pk_fma_f32 v[166:167], v[136:137], v[238:239], v[242:243]
	v_pk_mul_f32 v[134:135], v[160:161], v[160:161]
	v_pk_mul_f32 v[136:137], v[162:163], v[162:163]
	v_pk_fma_f32 v[134:135], v[134:135], s[54:55], 1.0 op_sel_hi:[1,0,0]
	v_pk_mul_f32 v[150:151], v[160:161], s[56:57] op_sel_hi:[1,0]
	v_pk_fma_f32 v[136:137], v[136:137], s[54:55], 1.0 op_sel_hi:[1,0,0]
	v_pk_mul_f32 v[152:153], v[162:163], s[56:57] op_sel_hi:[1,0]
	v_pk_mul_f32 v[134:135], v[150:151], v[134:135]
	v_pk_mul_f32 v[136:137], v[152:153], v[136:137]
	v_pk_mul_f32 v[134:135], v[134:135], s[58:59] op_sel_hi:[1,0]
	v_pk_mul_f32 v[136:137], v[136:137], s[58:59] op_sel_hi:[1,0]
	v_exp_f32_e32 v134, v134
	v_exp_f32_e32 v135, v135
	v_exp_f32_e32 v136, v136
	v_exp_f32_e32 v137, v137
	v_pk_add_f32 v[134:135], v[134:135], 1.0 op_sel_hi:[1,0]
	s_nop 0
	v_pk_add_f32 v[136:137], v[136:137], 1.0 op_sel_hi:[1,0]
	v_rcp_f32_e32 v134, v134
	v_rcp_f32_e32 v135, v135
	v_rcp_f32_e32 v136, v136
	v_rcp_f32_e32 v137, v137
	v_pk_mul_f32 v[134:135], v[160:161], v[134:135]
	v_pk_mul_f32 v[136:137], v[162:163], v[136:137]
	v_pk_mul_f32 v[134:135], v[164:165], v[134:135]
	v_pk_mul_f32 v[136:137], v[166:167], v[136:137]
	s_nop 0
	v_cvt_pk_bf16_f32 v130, v134, v135
	v_cvt_pk_bf16_f32 v131, v136, v137
	s_waitcnt lgkmcnt(4)
	v_pk_mul_f32 v[134:135], v[86:87], v[138:139] op_sel_hi:[1,0]
	v_pk_mul_f32 v[136:137], v[88:89], v[138:139] op_sel_hi:[1,0]
	v_pk_mul_f32 v[150:151], v[102:103], v[168:169] op_sel_hi:[1,0]
	v_pk_mul_f32 v[152:153], v[104:105], v[168:169] op_sel_hi:[1,0]
	v_cndmask_b32_e64 v154, v134, v150, s[4:5]
	v_cndmask_b32_e64 v155, v135, v151, s[4:5]
	v_cndmask_b32_e64 v156, v136, v152, s[4:5]
	v_cndmask_b32_e64 v157, v137, v153, s[4:5]
	v_cndmask_b32_e64 v150, v134, v150, s[2:3]
	v_cndmask_b32_e64 v151, v135, v151, s[2:3]
	v_cndmask_b32_e64 v152, v136, v152, s[2:3]
	v_cndmask_b32_e64 v153, v137, v153, s[2:3]
	v_fmac_f32_dpp v146, v150, v244 row_ror:2 row_mask:0xf bank_mask:0xf
	v_fmac_f32_dpp v147, v151, v245 row_ror:2 row_mask:0xf bank_mask:0xf
	v_fmac_f32_dpp v148, v152, v246 row_ror:2 row_mask:0xf bank_mask:0xf
	v_fmac_f32_dpp v149, v153, v247 row_ror:2 row_mask:0xf bank_mask:0xf
	v_fmac_f32_dpp v146, v154, v248 row_ror:1 row_mask:0xf bank_mask:0xf
	v_fmac_f32_dpp v147, v155, v249 row_ror:1 row_mask:0xf bank_mask:0xf
	v_fmac_f32_dpp v148, v156, v250 row_ror:1 row_mask:0xf bank_mask:0xf
	v_fmac_f32_dpp v149, v157, v251 row_ror:1 row_mask:0xf bank_mask:0xf
	v_pk_fma_f32 v[160:161], v[134:135], v[142:143], v[146:147]
	v_pk_fma_f32 v[162:163], v[136:137], v[144:145], v[148:149]
	s_waitcnt lgkmcnt(0)
	v_pk_mul_f32 v[134:135], v[82:83], v[138:139] op_sel_hi:[1,0]
	v_pk_mul_f32 v[136:137], v[84:85], v[138:139] op_sel_hi:[1,0]
	v_pk_mul_f32 v[150:151], v[98:99], v[168:169] op_sel_hi:[1,0]
	v_pk_mul_f32 v[152:153], v[100:101], v[168:169] op_sel_hi:[1,0]
	v_cndmask_b32_e64 v154, v134, v150, s[4:5]
	v_cndmask_b32_e64 v155, v135, v151, s[4:5]
	v_cndmask_b32_e64 v156, v136, v152, s[4:5]
	v_cndmask_b32_e64 v157, v137, v153, s[4:5]
	v_cndmask_b32_e64 v150, v134, v150, s[2:3]
	v_cndmask_b32_e64 v151, v135, v151, s[2:3]
	v_cndmask_b32_e64 v152, v136, v152, s[2:3]
	v_cndmask_b32_e64 v153, v137, v153, s[2:3]
	v_fmac_f32_dpp v216, v150, v204 row_ror:2 row_mask:0xf bank_mask:0xf
	v_fmac_f32_dpp v217, v151, v205 row_ror:2 row_mask:0xf bank_mask:0xf
	v_fmac_f32_dpp v218, v152, v206 row_ror:2 row_mask:0xf bank_mask:0xf
	v_fmac_f32_dpp v219, v153, v207 row_ror:2 row_mask:0xf bank_mask:0xf
	v_fmac_f32_dpp v216, v154, v208 row_ror:1 row_mask:0xf bank_mask:0xf
	v_fmac_f32_dpp v217, v155, v209 row_ror:1 row_mask:0xf bank_mask:0xf
	v_fmac_f32_dpp v218, v156, v210 row_ror:1 row_mask:0xf bank_mask:0xf
	v_fmac_f32_dpp v219, v157, v211 row_ror:1 row_mask:0xf bank_mask:0xf
	v_pk_fma_f32 v[164:165], v[134:135], v[212:213], v[216:217]
	v_pk_fma_f32 v[166:167], v[136:137], v[214:215], v[218:219]
	v_pk_mul_f32 v[134:135], v[160:161], v[160:161]
	v_pk_mul_f32 v[136:137], v[162:163], v[162:163]
	v_pk_fma_f32 v[134:135], v[134:135], s[54:55], 1.0 op_sel_hi:[1,0,0]
	v_pk_mul_f32 v[150:151], v[160:161], s[56:57] op_sel_hi:[1,0]
	v_pk_fma_f32 v[136:137], v[136:137], s[54:55], 1.0 op_sel_hi:[1,0,0]
	v_pk_mul_f32 v[152:153], v[162:163], s[56:57] op_sel_hi:[1,0]
	v_pk_mul_f32 v[134:135], v[150:151], v[134:135]
	v_pk_mul_f32 v[136:137], v[152:153], v[136:137]
	v_pk_mul_f32 v[134:135], v[134:135], s[58:59] op_sel_hi:[1,0]
	v_pk_mul_f32 v[136:137], v[136:137], s[58:59] op_sel_hi:[1,0]
	v_exp_f32_e32 v134, v134
	v_exp_f32_e32 v135, v135
	v_exp_f32_e32 v136, v136
	v_exp_f32_e32 v137, v137
	v_pk_add_f32 v[134:135], v[134:135], 1.0 op_sel_hi:[1,0]
	s_nop 0
	v_pk_add_f32 v[136:137], v[136:137], 1.0 op_sel_hi:[1,0]
	v_rcp_f32_e32 v134, v134
	v_rcp_f32_e32 v135, v135
	v_rcp_f32_e32 v136, v136
	v_rcp_f32_e32 v137, v137
	v_pk_mul_f32 v[134:135], v[160:161], v[134:135]
	v_pk_mul_f32 v[136:137], v[162:163], v[136:137]
	v_pk_mul_f32 v[134:135], v[164:165], v[134:135]
	v_pk_mul_f32 v[136:137], v[166:167], v[136:137]
	s_nop 0
	v_cvt_pk_bf16_f32 v132, v134, v135
	v_cvt_pk_bf16_f32 v133, v136, v137
	s_and_saveexec_b64 s[0:1], vcc
	s_cbranch_execz .LBB0_2610
	v_add_u32_e32 v136, s16, v158
	v_mov_b64_e32 v[134:135], s[50:51]
	v_mad_i64_i32 v[134:135], s[2:3], v136, s82, v[134:135]
	v_ashrrev_i32_e32 v141, 31, v140
	v_lshl_add_u64 v[134:135], s[36:37], 1, v[134:135]
	v_lshl_add_u64 v[134:135], v[140:141], 1, v[134:135]
	global_store_dwordx4 v[134:135], v[130:133], off
; #define GAS __attribute__((address_space(1)))
; #define LAS __attribute__((address_space(3)))
;     template <bool SAMPLE> __device__ __forceinline__ void body(const pg8::f32x4 (&acc)[2][2][4][2], const pg8::Unit& u, int wr, int fr, int cl0_, int acol0, LAS float* CW, LAS float* BD, LAS float* RSL) const {
;     ...
;                 const int fro = pg8_opq(fr), cl0 = pg8_opq(cl0_);
;                 const int rl = ai * 128 + wr * 64 + m * 16 + fro, row = u.pm * 256 + rl; const float rs = RSL[rl];
;                 v4u hw;
; #pragma unroll
;                 for (int n = 0; n < 2; ++n) {
;                     f32x4 cv2[2];
; #pragma unroll
;                     for (int bj = 0; bj < 2; ++bj) {
;                         const int cl = bj * 128 + cl0 + 4 * n, gcol = bj * DFF + acol0 + cl0 + 4 * n; const f32x4 x = acc[ai][bj][m][n] * rs;
;                         f32x4 s1, s2;
; #pragma unroll
;                         for (int i = 0; i < 4; ++i) { s1[i] = dpp_ror1(x[i]); s2[i] = dpp_ror2(x[i]); }
;                         if (SAMPLE) { const int t = fro & 3; const float* sp = state_conv + (size_t)((row - MP) >> 2) * 2 * UPW + gcol;
;                             const f32x4 S0 = *(const GAS f32x4*)sp, S1 = *(const GAS f32x4*)(sp + UPW);
; #pragma unroll
;                             for (int i = 0; i < 4; ++i) { s1[i] = (t >= 1) ? s1[i] : S1[i]; s2[i] = (t >= 2) ? s2[i] : (t == 1 ? S1[i] : S0[i]); }
;                             if (t >= 2) *(GAS f32x4*)(out + O_CVS + ((size_t)((row - MP) >> 2) * 2 + (t - 2)) * UPW + gcol) = x;
;                         } else if (m > 0) { const f32x4 xp = acc[ai][bj][m > 0 ? m - 1 : 0][n] * RSL[rl - 16];
; #pragma unroll
;                             for (int i = 0; i < 4; ++i) { s1[i] = dpp_ror1(fro == 15 ? xp[i] : x[i]); s2[i] = dpp_ror2(fro >= 14 ? xp[i] : x[i]); }
;                         } else { const int pb = (wr == 1) ? ai * 2 : 1;
;                             const int pr0 = (pb >> 1) * 128 + (pb & 1) * 64 + 62;
;                             const f32x4 b2 = *(const LAS f32x4*)(BD + (pb * 2 + 0) * 256 + cl) * RSL[pr0], b1 = *(const LAS f32x4*)(BD + (pb * 2 + 1) * 256 + cl) * RSL[pr0 + 1];
; #pragma unroll
;                             for (int i = 0; i < 4; ++i) { s1[i] = (fro >= 1) ? s1[i] : b1[i]; s2[i] = (fro >= 2) ? s2[i] : (fro == 1 ? b1[i] : b2[i]); }
;                         }
.LBB0_2610:
	s_or_b64 exec, exec, s[0:1]
	v_readlane_b32 s0, v255, 25
	v_mov_b32_e32 v140, v198
	v_lshl_add_u32 v141, v198, 2, 0
	v_cmp_eq_u32_e64 s[4:5], 15, v199
	v_cmp_lt_i32_e64 s[2:3], 13, v199
	v_add_u32_e32 v158, s0, v199
	v_add_u32_e32 v141, 0x20000, v141
	v_lshl_add_u32 v159, v158, 2, 0
	v_add_u32_e32 v159, 0x22fc0, v159
	ds_read_b32 v138, v159 offset:64
	ds_read_b32 v168, v159
	ds_read_b128 v[204:207], v141
	ds_read_b128 v[208:211], v141 offset:1024
	ds_read_b128 v[212:215], v141 offset:2048
	ds_read_b128 v[216:219], v141 offset:3072
	ds_read_b128 v[228:231], v141 offset:512
	ds_read_b128 v[232:235], v141 offset:1536
	ds_read_b128 v[236:239], v141 offset:2560
	ds_read_b128 v[240:243], v141 offset:3584
	v_cmp_lt_i32_e32 vcc, 1, v158
	ds_read_b128 v[244:247], v141 offset:16
	ds_read_b128 v[248:251], v141 offset:1040
	ds_read_b128 v[142:145], v141 offset:2064
	ds_read_b128 v[146:149], v141 offset:3088
	s_waitcnt lgkmcnt(8)
	v_pk_mul_f32 v[134:135], v[78:79], v[138:139] op_sel_hi:[1,0]
	v_pk_mul_f32 v[136:137], v[80:81], v[138:139] op_sel_hi:[1,0]
	v_pk_mul_f32 v[150:151], v[94:95], v[168:169] op_sel_hi:[1,0]
	v_pk_mul_f32 v[152:153], v[96:97], v[168:169] op_sel_hi:[1,0]
	v_cndmask_b32_e64 v154, v134, v150, s[4:5]
	v_cndmask_b32_e64 v155, v135, v151, s[4:5]
	v_cndmask_b32_e64 v156, v136, v152, s[4:5]
	v_cndmask_b32_e64 v157, v137, v153, s[4:5]
	v_cndmask_b32_e64 v150, v134, v150, s[2:3]
	v_cndmask_b32_e64 v151, v135, v151, s[2:3]
	v_cndmask_b32_e64 v152, v136, v152, s[2:3]
	v_cndmask_b32_e64 v153, v137, v153, s[2:3]
	v_fmac_f32_dpp v216, v150, v204 row_ror:2 row_mask:0xf bank_mask:0xf
	v_fmac_f32_dpp v217, v151, v205 row_ror:2 row_mask:0xf bank_mask:0xf
	v_fmac_f32_dpp v218, v152, v206 row_ror:2 row_mask:0xf bank_mask:0xf
	v_fmac_f32_dpp v219, v153, v207 row_ror:2 row_mask:0xf bank_mask:0xf
	v_fmac_f32_dpp v216, v154, v208 row_ror:1 row_mask:0xf bank_mask:0xf
	v_fmac_f32_dpp v217, v155, v209 row_ror:1 row_mask:0xf bank_mask:0xf
	v_fmac_f32_dpp v218, v156, v210 row_ror:1 row_mask:0xf bank_mask:0xf
	v_fmac_f32_dpp v219, v157, v211 row_ror:1 row_mask:0xf bank_mask:0xf
	v_pk_fma_f32 v[160:161], v[134:135], v[212:213], v[216:217]
	v_pk_fma_f32 v[162:163], v[136:137], v[214:215], v[218:219]
	ds_read_b128 v[204:207], v141 offset:528
	ds_read_b128 v[208:211], v141 offset:1552
	ds_read_b128 v[212:215], v141 offset:2576
	ds_read_b128 v[216:219], v141 offset:3600
	s_waitcnt lgkmcnt(8)
	v_pk_mul_f32 v[134:135], v[74:75], v[138:139] op_sel_hi:[1,0]
	v_pk_mul_f32 v[136:137], v[76:77], v[138:139] op_sel_hi:[1,0]
	v_pk_mul_f32 v[150:151], v[90:91], v[168:169] op_sel_hi:[1,0]
	v_pk_mul_f32 v[152:153], v[92:93], v[168:169] op_sel_hi:[1,0]
	v_cndmask_b32_e64 v154, v134, v150, s[4:5]
	v_cndmask_b32_e64 v155, v135, v151, s[4:5]
	v_cndmask_b32_e64 v156, v136, v152, s[4:5]
	v_cndmask_b32_e64 v157, v137, v153, s[4:5]
	v_cndmask_b32_e64 v150, v134, v150, s[2:3]
	v_cndmask_b32_e64 v151, v135, v151, s[2:3]
	v_cndmask_b32_e64 v152, v136, v152, s[2:3]
	v_cndmask_b32_e64 v153, v137, v153, s[2:3]
	v_fmac_f32_dpp v240, v150, v228 row_ror:2 row_mask:0xf bank_mask:0xf
	v_fmac_f32_dpp v241, v151, v229 row_ror:2 row_mask:0xf bank_mask:0xf
	v_fmac_f32_dpp v242, v152, v230 row_ror:2 row_mask:0xf bank_mask:0xf
	v_fmac_f32_dpp v243, v153, v231 row_ror:2 row_mask:0xf bank_mask:0xf
	v_fmac_f32_dpp v240, v154, v232 row_ror:1 row_mask:0xf bank_mask:0xf
	v_fmac_f32_dpp v241, v155, v233 row_ror:1 row_mask:0xf bank_mask:0xf
	v_fmac_f32_dpp v242, v156, v234 row_ror:1 row_mask:0xf bank_mask:0xf
	v_fmac_f32_dpp v243, v157, v235 row_ror:1 row_mask:0xf bank_mask:0xf
	v_pk_fma_f32 v[164:165], v[134:135], v[236:237], v[240:241]
	v_pk_fma_f32 v[166:167], v[136:137], v[238:239], v[242:243]
	v_pk_mul_f32 v[134:135], v[160:161], v[160:161]
	v_pk_mul_f32 v[136:137], v[162:163], v[162:163]
	v_pk_fma_f32 v[134:135], v[134:135], s[54:55], 1.0 op_sel_hi:[1,0,0]
	v_pk_mul_f32 v[150:151], v[160:161], s[56:57] op_sel_hi:[1,0]
	v_pk_fma_f32 v[136:137], v[136:137], s[54:55], 1.0 op_sel_hi:[1,0,0]
	v_pk_mul_f32 v[152:153], v[162:163], s[56:57] op_sel_hi:[1,0]
	v_pk_mul_f32 v[134:135], v[150:151], v[134:135]
	v_pk_mul_f32 v[136:137], v[152:153], v[136:137]
	v_pk_mul_f32 v[134:135], v[134:135], s[58:59] op_sel_hi:[1,0]
	v_pk_mul_f32 v[136:137], v[136:137], s[58:59] op_sel_hi:[1,0]
	v_exp_f32_e32 v134, v134
	v_exp_f32_e32 v135, v135
	v_exp_f32_e32 v136, v136
	v_exp_f32_e32 v137, v137
	v_pk_add_f32 v[134:135], v[134:135], 1.0 op_sel_hi:[1,0]
	s_nop 0
	v_pk_add_f32 v[136:137], v[136:137], 1.0 op_sel_hi:[1,0]
	v_rcp_f32_e32 v134, v134
	v_rcp_f32_e32 v135, v135
	v_rcp_f32_e32 v136, v136
	v_rcp_f32_e32 v137, v137
	v_pk_mul_f32 v[134:135], v[160:161], v[134:135]
	v_pk_mul_f32 v[136:137], v[162:163], v[136:137]
	v_pk_mul_f32 v[134:135], v[164:165], v[134:135]
	v_pk_mul_f32 v[136:137], v[166:167], v[136:137]
	s_nop 0
	v_cvt_pk_bf16_f32 v130, v134, v135
	v_cvt_pk_bf16_f32 v131, v136, v137
	s_waitcnt lgkmcnt(4)
; #define GAS __attribute__((address_space(1)))
; #define LAS __attribute__((address_space(3)))
;     template <bool SAMPLE> __device__ __forceinline__ void body(const pg8::f32x4 (&acc)[2][2][4][2], const pg8::Unit& u, int wr, int fr, int cl0_, int acol0, LAS float* CW, LAS float* BD, LAS float* RSL) const {
;     ...
;                 const int fro = pg8_opq(fr), cl0 = pg8_opq(cl0_);
;                 const int rl = ai * 128 + wr * 64 + m * 16 + fro, row = u.pm * 256 + rl; const float rs = RSL[rl];
;                 v4u hw;
; #pragma unroll
;                 for (int n = 0; n < 2; ++n) {
;                     f32x4 cv2[2];
; #pragma unroll
;                     for (int bj = 0; bj < 2; ++bj) {
;                         const int cl = bj * 128 + cl0 + 4 * n, gcol = bj * DFF + acol0 + cl0 + 4 * n; const f32x4 x = acc[ai][bj][m][n] * rs;
;                         f32x4 s1, s2;
; #pragma unroll
;                         for (int i = 0; i < 4; ++i) { s1[i] = dpp_ror1(x[i]); s2[i] = dpp_ror2(x[i]); }
;                         if (SAMPLE) { const int t = fro & 3; const float* sp = state_conv + (size_t)((row - MP) >> 2) * 2 * UPW + gcol;
;                             const f32x4 S0 = *(const GAS f32x4*)sp, S1 = *(const GAS f32x4*)(sp + UPW);
; #pragma unroll
;                             for (int i = 0; i < 4; ++i) { s1[i] = (t >= 1) ? s1[i] : S1[i]; s2[i] = (t >= 2) ? s2[i] : (t == 1 ? S1[i] : S0[i]); }
;                             if (t >= 2) *(GAS f32x4*)(out + O_CVS + ((size_t)((row - MP) >> 2) * 2 + (t - 2)) * UPW + gcol) = x;
;                         } else if (m > 0) { const f32x4 xp = acc[ai][bj][m > 0 ? m - 1 : 0][n] * RSL[rl - 16];
; #pragma unroll
;                             for (int i = 0; i < 4; ++i) { s1[i] = dpp_ror1(fro == 15 ? xp[i] : x[i]); s2[i] = dpp_ror2(fro >= 14 ? xp[i] : x[i]); }
;                         } else { const int pb = (wr == 1) ? ai * 2 : 1;
;                             const int pr0 = (pb >> 1) * 128 + (pb & 1) * 64 + 62;
;                             const f32x4 b2 = *(const LAS f32x4*)(BD + (pb * 2 + 0) * 256 + cl) * RSL[pr0], b1 = *(const LAS f32x4*)(BD + (pb * 2 + 1) * 256 + cl) * RSL[pr0 + 1];
; #pragma unroll
;                             for (int i = 0; i < 4; ++i) { s1[i] = (fro >= 1) ? s1[i] : b1[i]; s2[i] = (fro >= 2) ? s2[i] : (fro == 1 ? b1[i] : b2[i]); }
;                         }
	v_pk_mul_f32 v[134:135], v[70:71], v[138:139] op_sel_hi:[1,0]
	v_pk_mul_f32 v[136:137], v[72:73], v[138:139] op_sel_hi:[1,0]
	v_pk_mul_f32 v[150:151], v[86:87], v[168:169] op_sel_hi:[1,0]
	v_pk_mul_f32 v[152:153], v[88:89], v[168:169] op_sel_hi:[1,0]
	v_cndmask_b32_e64 v154, v134, v150, s[4:5]
	v_cndmask_b32_e64 v155, v135, v151, s[4:5]
	v_cndmask_b32_e64 v156, v136, v152, s[4:5]
	v_cndmask_b32_e64 v157, v137, v153, s[4:5]
	v_cndmask_b32_e64 v150, v134, v150, s[2:3]
	v_cndmask_b32_e64 v151, v135, v151, s[2:3]
	v_cndmask_b32_e64 v152, v136, v152, s[2:3]
	v_cndmask_b32_e64 v153, v137, v153, s[2:3]
	v_fmac_f32_dpp v146, v150, v244 row_ror:2 row_mask:0xf bank_mask:0xf
	v_fmac_f32_dpp v147, v151, v245 row_ror:2 row_mask:0xf bank_mask:0xf
	v_fmac_f32_dpp v148, v152, v246 row_ror:2 row_mask:0xf bank_mask:0xf
	v_fmac_f32_dpp v149, v153, v247 row_ror:2 row_mask:0xf bank_mask:0xf
	v_fmac_f32_dpp v146, v154, v248 row_ror:1 row_mask:0xf bank_mask:0xf
	v_fmac_f32_dpp v147, v155, v249 row_ror:1 row_mask:0xf bank_mask:0xf
	v_fmac_f32_dpp v148, v156, v250 row_ror:1 row_mask:0xf bank_mask:0xf
	v_fmac_f32_dpp v149, v157, v251 row_ror:1 row_mask:0xf bank_mask:0xf
	v_pk_fma_f32 v[160:161], v[134:135], v[142:143], v[146:147]
	v_pk_fma_f32 v[162:163], v[136:137], v[144:145], v[148:149]
	s_waitcnt lgkmcnt(0)
	v_pk_mul_f32 v[134:135], v[66:67], v[138:139] op_sel_hi:[1,0]
	v_pk_mul_f32 v[136:137], v[68:69], v[138:139] op_sel_hi:[1,0]
	v_pk_mul_f32 v[150:151], v[82:83], v[168:169] op_sel_hi:[1,0]
	v_pk_mul_f32 v[152:153], v[84:85], v[168:169] op_sel_hi:[1,0]
	v_cndmask_b32_e64 v154, v134, v150, s[4:5]
	v_cndmask_b32_e64 v155, v135, v151, s[4:5]
	v_cndmask_b32_e64 v156, v136, v152, s[4:5]
	v_cndmask_b32_e64 v157, v137, v153, s[4:5]
	v_cndmask_b32_e64 v150, v134, v150, s[2:3]
	v_cndmask_b32_e64 v151, v135, v151, s[2:3]
	v_cndmask_b32_e64 v152, v136, v152, s[2:3]
	v_cndmask_b32_e64 v153, v137, v153, s[2:3]
	v_fmac_f32_dpp v216, v150, v204 row_ror:2 row_mask:0xf bank_mask:0xf
	v_fmac_f32_dpp v217, v151, v205 row_ror:2 row_mask:0xf bank_mask:0xf
	v_fmac_f32_dpp v218, v152, v206 row_ror:2 row_mask:0xf bank_mask:0xf
	v_fmac_f32_dpp v219, v153, v207 row_ror:2 row_mask:0xf bank_mask:0xf
	v_fmac_f32_dpp v216, v154, v208 row_ror:1 row_mask:0xf bank_mask:0xf
	v_fmac_f32_dpp v217, v155, v209 row_ror:1 row_mask:0xf bank_mask:0xf
	v_fmac_f32_dpp v218, v156, v210 row_ror:1 row_mask:0xf bank_mask:0xf
	v_fmac_f32_dpp v219, v157, v211 row_ror:1 row_mask:0xf bank_mask:0xf
	v_pk_fma_f32 v[164:165], v[134:135], v[212:213], v[216:217]
	v_pk_fma_f32 v[166:167], v[136:137], v[214:215], v[218:219]
	v_pk_mul_f32 v[134:135], v[160:161], v[160:161]
	v_pk_mul_f32 v[136:137], v[162:163], v[162:163]
	v_pk_fma_f32 v[134:135], v[134:135], s[54:55], 1.0 op_sel_hi:[1,0,0]
	v_pk_mul_f32 v[150:151], v[160:161], s[56:57] op_sel_hi:[1,0]
	v_pk_fma_f32 v[136:137], v[136:137], s[54:55], 1.0 op_sel_hi:[1,0,0]
	v_pk_mul_f32 v[152:153], v[162:163], s[56:57] op_sel_hi:[1,0]
	v_pk_mul_f32 v[134:135], v[150:151], v[134:135]
	v_pk_mul_f32 v[136:137], v[152:153], v[136:137]
	v_pk_mul_f32 v[134:135], v[134:135], s[58:59] op_sel_hi:[1,0]
	v_pk_mul_f32 v[136:137], v[136:137], s[58:59] op_sel_hi:[1,0]
	v_exp_f32_e32 v134, v134
	v_exp_f32_e32 v135, v135
	v_exp_f32_e32 v136, v136
	v_exp_f32_e32 v137, v137
	v_pk_add_f32 v[134:135], v[134:135], 1.0 op_sel_hi:[1,0]
	s_nop 0
	v_pk_add_f32 v[136:137], v[136:137], 1.0 op_sel_hi:[1,0]
	v_rcp_f32_e32 v134, v134
	v_rcp_f32_e32 v135, v135
	v_rcp_f32_e32 v136, v136
	v_rcp_f32_e32 v137, v137
	v_pk_mul_f32 v[134:135], v[160:161], v[134:135]
	v_pk_mul_f32 v[136:137], v[162:163], v[136:137]
	v_pk_mul_f32 v[134:135], v[164:165], v[134:135]
	v_pk_mul_f32 v[136:137], v[166:167], v[136:137]
	s_nop 0
	v_cvt_pk_bf16_f32 v132, v134, v135
	v_cvt_pk_bf16_f32 v133, v136, v137
	s_and_saveexec_b64 s[0:1], vcc
	s_cbranch_execz .LBB0_2612
	v_add_u32_e32 v136, s16, v158
	v_mov_b64_e32 v[134:135], s[50:51]
	v_mad_i64_i32 v[134:135], s[2:3], v136, s82, v[134:135]
	v_ashrrev_i32_e32 v141, 31, v140
	v_lshl_add_u64 v[134:135], s[36:37], 1, v[134:135]
	v_lshl_add_u64 v[134:135], v[140:141], 1, v[134:135]
	global_store_dwordx4 v[134:135], v[130:133], off

; #define GAS __attribute__((address_space(1)))
; #define LAS __attribute__((address_space(3)))
;     template <bool SAMPLE> __device__ __forceinline__ void body(const pg8::f32x4 (&acc)[2][2][4][2], const pg8::Unit& u, int wr, int fr, int cl0_, int acol0, LAS float* CW, LAS float* BD, LAS float* RSL) const {
;     ...
;                 const int fro = pg8_opq(fr), cl0 = pg8_opq(cl0_);
;                 const int rl = ai * 128 + wr * 64 + m * 16 + fro, row = u.pm * 256 + rl; const float rs = RSL[rl];
;                 v4u hw;
; #pragma unroll
;                 for (int n = 0; n < 2; ++n) {
;                     f32x4 cv2[2];
; #pragma unroll
;                     for (int bj = 0; bj < 2; ++bj) {
;                         const int cl = bj * 128 + cl0 + 4 * n, gcol = bj * DFF + acol0 + cl0 + 4 * n; const f32x4 x = acc[ai][bj][m][n] * rs;
;                         f32x4 s1, s2;
; #pragma unroll
;                         for (int i = 0; i < 4; ++i) { s1[i] = dpp_ror1(x[i]); s2[i] = dpp_ror2(x[i]); }
;                         if (SAMPLE) { const int t = fro & 3; const float* sp = state_conv + (size_t)((row - MP) >> 2) * 2 * UPW + gcol;
;                             const f32x4 S0 = *(const GAS f32x4*)sp, S1 = *(const GAS f32x4*)(sp + UPW);
; #pragma unroll
;                             for (int i = 0; i < 4; ++i) { s1[i] = (t >= 1) ? s1[i] : S1[i]; s2[i] = (t >= 2) ? s2[i] : (t == 1 ? S1[i] : S0[i]); }
;                             if (t >= 2) *(GAS f32x4*)(out + O_CVS + ((size_t)((row - MP) >> 2) * 2 + (t - 2)) * UPW + gcol) = x;
;                         } else if (m > 0) { const f32x4 xp = acc[ai][bj][m > 0 ? m - 1 : 0][n] * RSL[rl - 16];
; #pragma unroll
;                             for (int i = 0; i < 4; ++i) { s1[i] = dpp_ror1(fro == 15 ? xp[i] : x[i]); s2[i] = dpp_ror2(fro >= 14 ? xp[i] : x[i]); }
;                         } else { const int pb = (wr == 1) ? ai * 2 : 1;
;                             const int pr0 = (pb >> 1) * 128 + (pb & 1) * 64 + 62;
;                             const f32x4 b2 = *(const LAS f32x4*)(BD + (pb * 2 + 0) * 256 + cl) * RSL[pr0], b1 = *(const LAS f32x4*)(BD + (pb * 2 + 1) * 256 + cl) * RSL[pr0 + 1];
; #pragma unroll
;                             for (int i = 0; i < 4; ++i) { s1[i] = (fro >= 1) ? s1[i] : b1[i]; s2[i] = (fro >= 2) ? s2[i] : (fro == 1 ? b1[i] : b2[i]); }
;                         }
.LBB0_2614:
	s_or_b64 exec, exec, s[0:1]
	v_mov_b32_e32 v140, v198
	v_lshl_add_u32 v141, v198, 2, 0
	v_cmp_eq_u32_e64 s[4:5], 15, v199
	v_cmp_lt_i32_e64 s[2:3], 13, v199
	v_add_u32_e32 v158, s27, v199
	v_add_u32_e32 v141, 0x20000, v141
	v_lshl_add_u32 v159, v158, 2, 0
	v_add_u32_e32 v159, 0x22fc0, v159
	ds_read_b32 v138, v159 offset:64
	ds_read_b32 v168, v159
	ds_read_b128 v[204:207], v141
	ds_read_b128 v[208:211], v141 offset:1024
	ds_read_b128 v[212:215], v141 offset:2048
	ds_read_b128 v[216:219], v141 offset:3072
	ds_read_b128 v[228:231], v141 offset:512
	ds_read_b128 v[232:235], v141 offset:1536
	ds_read_b128 v[236:239], v141 offset:2560
	ds_read_b128 v[240:243], v141 offset:3584
	v_cmp_lt_i32_e32 vcc, 1, v158
	ds_read_b128 v[244:247], v141 offset:16
	ds_read_b128 v[248:251], v141 offset:1040
	ds_read_b128 v[142:145], v141 offset:2064
	ds_read_b128 v[146:149], v141 offset:3088
	s_waitcnt lgkmcnt(8)
	v_pk_mul_f32 v[134:135], v[46:47], v[138:139] op_sel_hi:[1,0]
	v_pk_mul_f32 v[136:137], v[48:49], v[138:139] op_sel_hi:[1,0]
	v_pk_mul_f32 v[150:151], v[62:63], v[168:169] op_sel_hi:[1,0]
	v_pk_mul_f32 v[152:153], v[64:65], v[168:169] op_sel_hi:[1,0]
	v_cndmask_b32_e64 v154, v134, v150, s[4:5]
	v_cndmask_b32_e64 v155, v135, v151, s[4:5]
	v_cndmask_b32_e64 v156, v136, v152, s[4:5]
	v_cndmask_b32_e64 v157, v137, v153, s[4:5]
	v_cndmask_b32_e64 v150, v134, v150, s[2:3]
	v_cndmask_b32_e64 v151, v135, v151, s[2:3]
	v_cndmask_b32_e64 v152, v136, v152, s[2:3]
	v_cndmask_b32_e64 v153, v137, v153, s[2:3]
	v_fmac_f32_dpp v216, v150, v204 row_ror:2 row_mask:0xf bank_mask:0xf
	v_fmac_f32_dpp v217, v151, v205 row_ror:2 row_mask:0xf bank_mask:0xf
	v_fmac_f32_dpp v218, v152, v206 row_ror:2 row_mask:0xf bank_mask:0xf
	v_fmac_f32_dpp v219, v153, v207 row_ror:2 row_mask:0xf bank_mask:0xf
	v_fmac_f32_dpp v216, v154, v208 row_ror:1 row_mask:0xf bank_mask:0xf
	v_fmac_f32_dpp v217, v155, v209 row_ror:1 row_mask:0xf bank_mask:0xf
	v_fmac_f32_dpp v218, v156, v210 row_ror:1 row_mask:0xf bank_mask:0xf
	v_fmac_f32_dpp v219, v157, v211 row_ror:1 row_mask:0xf bank_mask:0xf
	v_pk_fma_f32 v[160:161], v[134:135], v[212:213], v[216:217]
	v_pk_fma_f32 v[162:163], v[136:137], v[214:215], v[218:219]
	ds_read_b128 v[204:207], v141 offset:528
	ds_read_b128 v[208:211], v141 offset:1552
	ds_read_b128 v[212:215], v141 offset:2576
	ds_read_b128 v[216:219], v141 offset:3600
	s_waitcnt lgkmcnt(8)
	v_pk_mul_f32 v[134:135], v[42:43], v[138:139] op_sel_hi:[1,0]
	v_pk_mul_f32 v[136:137], v[44:45], v[138:139] op_sel_hi:[1,0]
	v_pk_mul_f32 v[150:151], v[58:59], v[168:169] op_sel_hi:[1,0]
	v_pk_mul_f32 v[152:153], v[60:61], v[168:169] op_sel_hi:[1,0]
	v_cndmask_b32_e64 v154, v134, v150, s[4:5]
	v_cndmask_b32_e64 v155, v135, v151, s[4:5]
	v_cndmask_b32_e64 v156, v136, v152, s[4:5]
	v_cndmask_b32_e64 v157, v137, v153, s[4:5]
	v_cndmask_b32_e64 v150, v134, v150, s[2:3]
	v_cndmask_b32_e64 v151, v135, v151, s[2:3]
	v_cndmask_b32_e64 v152, v136, v152, s[2:3]
	v_cndmask_b32_e64 v153, v137, v153, s[2:3]
	v_fmac_f32_dpp v240, v150, v228 row_ror:2 row_mask:0xf bank_mask:0xf
	v_fmac_f32_dpp v241, v151, v229 row_ror:2 row_mask:0xf bank_mask:0xf
	v_fmac_f32_dpp v242, v152, v230 row_ror:2 row_mask:0xf bank_mask:0xf
	v_fmac_f32_dpp v243, v153, v231 row_ror:2 row_mask:0xf bank_mask:0xf
	v_fmac_f32_dpp v240, v154, v232 row_ror:1 row_mask:0xf bank_mask:0xf
	v_fmac_f32_dpp v241, v155, v233 row_ror:1 row_mask:0xf bank_mask:0xf
	v_fmac_f32_dpp v242, v156, v234 row_ror:1 row_mask:0xf bank_mask:0xf
	v_fmac_f32_dpp v243, v157, v235 row_ror:1 row_mask:0xf bank_mask:0xf
	v_pk_fma_f32 v[164:165], v[134:135], v[236:237], v[240:241]
	v_pk_fma_f32 v[166:167], v[136:137], v[238:239], v[242:243]
	v_pk_mul_f32 v[134:135], v[160:161], v[160:161]
	v_pk_mul_f32 v[136:137], v[162:163], v[162:163]
	v_pk_fma_f32 v[134:135], v[134:135], s[54:55], 1.0 op_sel_hi:[1,0,0]
	v_pk_mul_f32 v[150:151], v[160:161], s[56:57] op_sel_hi:[1,0]
	v_pk_fma_f32 v[136:137], v[136:137], s[54:55], 1.0 op_sel_hi:[1,0,0]
	v_pk_mul_f32 v[152:153], v[162:163], s[56:57] op_sel_hi:[1,0]
	v_pk_mul_f32 v[134:135], v[150:151], v[134:135]
	v_pk_mul_f32 v[136:137], v[152:153], v[136:137]
	v_pk_mul_f32 v[134:135], v[134:135], s[58:59] op_sel_hi:[1,0]
	v_pk_mul_f32 v[136:137], v[136:137], s[58:59] op_sel_hi:[1,0]
	v_exp_f32_e32 v134, v134
	v_exp_f32_e32 v135, v135
	v_exp_f32_e32 v136, v136
	v_exp_f32_e32 v137, v137
	v_pk_add_f32 v[134:135], v[134:135], 1.0 op_sel_hi:[1,0]
	s_nop 0
	v_pk_add_f32 v[136:137], v[136:137], 1.0 op_sel_hi:[1,0]
	v_rcp_f32_e32 v134, v134
	v_rcp_f32_e32 v135, v135
	v_rcp_f32_e32 v136, v136
	v_rcp_f32_e32 v137, v137
	v_pk_mul_f32 v[134:135], v[160:161], v[134:135]
	v_pk_mul_f32 v[136:137], v[162:163], v[136:137]
	v_pk_mul_f32 v[134:135], v[164:165], v[134:135]
	v_pk_mul_f32 v[136:137], v[166:167], v[136:137]
	s_nop 0
	v_cvt_pk_bf16_f32 v130, v134, v135
	v_cvt_pk_bf16_f32 v131, v136, v137
	s_waitcnt lgkmcnt(4)
	v_pk_mul_f32 v[134:135], v[38:39], v[138:139] op_sel_hi:[1,0]
	v_pk_mul_f32 v[136:137], v[40:41], v[138:139] op_sel_hi:[1,0]
	v_pk_mul_f32 v[150:151], v[54:55], v[168:169] op_sel_hi:[1,0]
	v_pk_mul_f32 v[152:153], v[56:57], v[168:169] op_sel_hi:[1,0]
	v_cndmask_b32_e64 v154, v134, v150, s[4:5]
	v_cndmask_b32_e64 v155, v135, v151, s[4:5]
	v_cndmask_b32_e64 v156, v136, v152, s[4:5]
	v_cndmask_b32_e64 v157, v137, v153, s[4:5]
	v_cndmask_b32_e64 v150, v134, v150, s[2:3]
	v_cndmask_b32_e64 v151, v135, v151, s[2:3]
	v_cndmask_b32_e64 v152, v136, v152, s[2:3]
	v_cndmask_b32_e64 v153, v137, v153, s[2:3]
	v_fmac_f32_dpp v146, v150, v244 row_ror:2 row_mask:0xf bank_mask:0xf
	v_fmac_f32_dpp v147, v151, v245 row_ror:2 row_mask:0xf bank_mask:0xf
	v_fmac_f32_dpp v148, v152, v246 row_ror:2 row_mask:0xf bank_mask:0xf
	v_fmac_f32_dpp v149, v153, v247 row_ror:2 row_mask:0xf bank_mask:0xf
	v_fmac_f32_dpp v146, v154, v248 row_ror:1 row_mask:0xf bank_mask:0xf
	v_fmac_f32_dpp v147, v155, v249 row_ror:1 row_mask:0xf bank_mask:0xf
	v_fmac_f32_dpp v148, v156, v250 row_ror:1 row_mask:0xf bank_mask:0xf
	v_fmac_f32_dpp v149, v157, v251 row_ror:1 row_mask:0xf bank_mask:0xf
	v_pk_fma_f32 v[160:161], v[134:135], v[142:143], v[146:147]
	v_pk_fma_f32 v[162:163], v[136:137], v[144:145], v[148:149]
	s_waitcnt lgkmcnt(0)
; #define GAS __attribute__((address_space(1)))
; #define LAS __attribute__((address_space(3)))
;     template <bool SAMPLE> __device__ __forceinline__ void body(const pg8::f32x4 (&acc)[2][2][4][2], const pg8::Unit& u, int wr, int fr, int cl0_, int acol0, LAS float* CW, LAS float* BD, LAS float* RSL) const {
;     ...
;                 const int fro = pg8_opq(fr), cl0 = pg8_opq(cl0_);
;                 const int rl = ai * 128 + wr * 64 + m * 16 + fro, row = u.pm * 256 + rl; const float rs = RSL[rl];
;                 v4u hw;
; #pragma unroll
;                 for (int n = 0; n < 2; ++n) {
;                     f32x4 cv2[2];
; #pragma unroll
;                     for (int bj = 0; bj < 2; ++bj) {
;                         const int cl = bj * 128 + cl0 + 4 * n, gcol = bj * DFF + acol0 + cl0 + 4 * n; const f32x4 x = acc[ai][bj][m][n] * rs;
;                         f32x4 s1, s2;
; #pragma unroll
;                         for (int i = 0; i < 4; ++i) { s1[i] = dpp_ror1(x[i]); s2[i] = dpp_ror2(x[i]); }
;                         if (SAMPLE) { const int t = fro & 3; const float* sp = state_conv + (size_t)((row - MP) >> 2) * 2 * UPW + gcol;
;                             const f32x4 S0 = *(const GAS f32x4*)sp, S1 = *(const GAS f32x4*)(sp + UPW);
; #pragma unroll
;                             for (int i = 0; i < 4; ++i) { s1[i] = (t >= 1) ? s1[i] : S1[i]; s2[i] = (t >= 2) ? s2[i] : (t == 1 ? S1[i] : S0[i]); }
;                             if (t >= 2) *(GAS f32x4*)(out + O_CVS + ((size_t)((row - MP) >> 2) * 2 + (t - 2)) * UPW + gcol) = x;
;                         } else if (m > 0) { const f32x4 xp = acc[ai][bj][m > 0 ? m - 1 : 0][n] * RSL[rl - 16];
; #pragma unroll
;                             for (int i = 0; i < 4; ++i) { s1[i] = dpp_ror1(fro == 15 ? xp[i] : x[i]); s2[i] = dpp_ror2(fro >= 14 ? xp[i] : x[i]); }
;                         } else { const int pb = (wr == 1) ? ai * 2 : 1;
;                             const int pr0 = (pb >> 1) * 128 + (pb & 1) * 64 + 62;
;                             const f32x4 b2 = *(const LAS f32x4*)(BD + (pb * 2 + 0) * 256 + cl) * RSL[pr0], b1 = *(const LAS f32x4*)(BD + (pb * 2 + 1) * 256 + cl) * RSL[pr0 + 1];
; #pragma unroll
;                             for (int i = 0; i < 4; ++i) { s1[i] = (fro >= 1) ? s1[i] : b1[i]; s2[i] = (fro >= 2) ? s2[i] : (fro == 1 ? b1[i] : b2[i]); }
;                         }
	v_pk_mul_f32 v[134:135], v[34:35], v[138:139] op_sel_hi:[1,0]
	v_pk_mul_f32 v[136:137], v[36:37], v[138:139] op_sel_hi:[1,0]
	v_pk_mul_f32 v[150:151], v[50:51], v[168:169] op_sel_hi:[1,0]
	v_pk_mul_f32 v[152:153], v[52:53], v[168:169] op_sel_hi:[1,0]
	v_cndmask_b32_e64 v154, v134, v150, s[4:5]
	v_cndmask_b32_e64 v155, v135, v151, s[4:5]
	v_cndmask_b32_e64 v156, v136, v152, s[4:5]
	v_cndmask_b32_e64 v157, v137, v153, s[4:5]
	v_cndmask_b32_e64 v150, v134, v150, s[2:3]
	v_cndmask_b32_e64 v151, v135, v151, s[2:3]
	v_cndmask_b32_e64 v152, v136, v152, s[2:3]
	v_cndmask_b32_e64 v153, v137, v153, s[2:3]
	v_fmac_f32_dpp v216, v150, v204 row_ror:2 row_mask:0xf bank_mask:0xf
	v_fmac_f32_dpp v217, v151, v205 row_ror:2 row_mask:0xf bank_mask:0xf
	v_fmac_f32_dpp v218, v152, v206 row_ror:2 row_mask:0xf bank_mask:0xf
	v_fmac_f32_dpp v219, v153, v207 row_ror:2 row_mask:0xf bank_mask:0xf
	v_fmac_f32_dpp v216, v154, v208 row_ror:1 row_mask:0xf bank_mask:0xf
	v_fmac_f32_dpp v217, v155, v209 row_ror:1 row_mask:0xf bank_mask:0xf
	v_fmac_f32_dpp v218, v156, v210 row_ror:1 row_mask:0xf bank_mask:0xf
	v_fmac_f32_dpp v219, v157, v211 row_ror:1 row_mask:0xf bank_mask:0xf
	v_pk_fma_f32 v[164:165], v[134:135], v[212:213], v[216:217]
	v_pk_fma_f32 v[166:167], v[136:137], v[214:215], v[218:219]
	v_pk_mul_f32 v[134:135], v[160:161], v[160:161]
	v_pk_mul_f32 v[136:137], v[162:163], v[162:163]
	v_pk_fma_f32 v[134:135], v[134:135], s[54:55], 1.0 op_sel_hi:[1,0,0]
	v_pk_mul_f32 v[150:151], v[160:161], s[56:57] op_sel_hi:[1,0]
	v_pk_fma_f32 v[136:137], v[136:137], s[54:55], 1.0 op_sel_hi:[1,0,0]
	v_pk_mul_f32 v[152:153], v[162:163], s[56:57] op_sel_hi:[1,0]
	v_pk_mul_f32 v[134:135], v[150:151], v[134:135]
	v_pk_mul_f32 v[136:137], v[152:153], v[136:137]
	v_pk_mul_f32 v[134:135], v[134:135], s[58:59] op_sel_hi:[1,0]
	v_pk_mul_f32 v[136:137], v[136:137], s[58:59] op_sel_hi:[1,0]
	v_exp_f32_e32 v134, v134
	v_exp_f32_e32 v135, v135
	v_exp_f32_e32 v136, v136
	v_exp_f32_e32 v137, v137
	v_pk_add_f32 v[134:135], v[134:135], 1.0 op_sel_hi:[1,0]
	s_nop 0
	v_pk_add_f32 v[136:137], v[136:137], 1.0 op_sel_hi:[1,0]
	v_rcp_f32_e32 v134, v134
	v_rcp_f32_e32 v135, v135
	v_rcp_f32_e32 v136, v136
	v_rcp_f32_e32 v137, v137
	v_pk_mul_f32 v[134:135], v[160:161], v[134:135]
	v_pk_mul_f32 v[136:137], v[162:163], v[136:137]
	v_pk_mul_f32 v[134:135], v[164:165], v[134:135]
	v_pk_mul_f32 v[136:137], v[166:167], v[136:137]
	s_nop 0
	v_cvt_pk_bf16_f32 v132, v134, v135
	v_cvt_pk_bf16_f32 v133, v136, v137
	s_and_saveexec_b64 s[0:1], vcc
	s_cbranch_execz .LBB0_2616
	v_add_u32_e32 v136, s16, v158
	v_mov_b64_e32 v[134:135], s[50:51]
	v_mad_i64_i32 v[134:135], s[2:3], v136, s82, v[134:135]
	v_ashrrev_i32_e32 v141, 31, v140
	v_lshl_add_u64 v[134:135], s[36:37], 1, v[134:135]
	v_lshl_add_u64 v[134:135], v[140:141], 1, v[134:135]
	global_store_dwordx4 v[134:135], v[130:133], off
.LBB0_2616:
	s_or_b64 exec, exec, s[0:1]
	v_mov_b32_e32 v140, v198
	v_lshl_add_u32 v141, v198, 2, 0
	v_cmp_eq_u32_e64 s[4:5], 15, v199
	v_cmp_lt_i32_e64 s[2:3], 13, v199
	v_add_u32_e32 v158, s34, v199
	v_add_u32_e32 v141, 0x20000, v141
	v_lshl_add_u32 v159, v158, 2, 0
	v_add_u32_e32 v159, 0x22fc0, v159
	ds_read_b32 v138, v159 offset:64
	ds_read_b32 v168, v159
	ds_read_b128 v[204:207], v141
	ds_read_b128 v[208:211], v141 offset:1024
	ds_read_b128 v[212:215], v141 offset:2048
	ds_read_b128 v[216:219], v141 offset:3072
	ds_read_b128 v[228:231], v141 offset:512
	ds_read_b128 v[232:235], v141 offset:1536
	ds_read_b128 v[236:239], v141 offset:2560
	ds_read_b128 v[240:243], v141 offset:3584
	v_cmp_lt_i32_e32 vcc, 1, v158
	ds_read_b128 v[244:247], v141 offset:16
	ds_read_b128 v[248:251], v141 offset:1040
	ds_read_b128 v[142:145], v141 offset:2064
	ds_read_b128 v[146:149], v141 offset:3088
	s_waitcnt lgkmcnt(8)
	v_pk_mul_f32 v[134:135], v[30:31], v[138:139] op_sel_hi:[1,0]
	v_pk_mul_f32 v[136:137], v[32:33], v[138:139] op_sel_hi:[1,0]
	v_pk_mul_f32 v[150:151], v[46:47], v[168:169] op_sel_hi:[1,0]
	v_pk_mul_f32 v[152:153], v[48:49], v[168:169] op_sel_hi:[1,0]
	v_cndmask_b32_e64 v154, v134, v150, s[4:5]
	v_cndmask_b32_e64 v155, v135, v151, s[4:5]
	v_cndmask_b32_e64 v156, v136, v152, s[4:5]
	v_cndmask_b32_e64 v157, v137, v153, s[4:5]
	v_cndmask_b32_e64 v150, v134, v150, s[2:3]
	v_cndmask_b32_e64 v151, v135, v151, s[2:3]
	v_cndmask_b32_e64 v152, v136, v152, s[2:3]
	v_cndmask_b32_e64 v153, v137, v153, s[2:3]
	v_fmac_f32_dpp v216, v150, v204 row_ror:2 row_mask:0xf bank_mask:0xf
	v_fmac_f32_dpp v217, v151, v205 row_ror:2 row_mask:0xf bank_mask:0xf
	v_fmac_f32_dpp v218, v152, v206 row_ror:2 row_mask:0xf bank_mask:0xf
	v_fmac_f32_dpp v219, v153, v207 row_ror:2 row_mask:0xf bank_mask:0xf
	v_fmac_f32_dpp v216, v154, v208 row_ror:1 row_mask:0xf bank_mask:0xf
	v_fmac_f32_dpp v217, v155, v209 row_ror:1 row_mask:0xf bank_mask:0xf
	v_fmac_f32_dpp v218, v156, v210 row_ror:1 row_mask:0xf bank_mask:0xf
	v_fmac_f32_dpp v219, v157, v211 row_ror:1 row_mask:0xf bank_mask:0xf
	v_pk_fma_f32 v[160:161], v[134:135], v[212:213], v[216:217]
	v_pk_fma_f32 v[162:163], v[136:137], v[214:215], v[218:219]
	ds_read_b128 v[204:207], v141 offset:528
	ds_read_b128 v[208:211], v141 offset:1552
	ds_read_b128 v[212:215], v141 offset:2576
	ds_read_b128 v[216:219], v141 offset:3600
	s_waitcnt lgkmcnt(8)
;     template <bool SAMPLE> __device__ __forceinline__ void body(const pg8::f32x4 (&acc)[2][2][4][2], const pg8::Unit& u, int wr, int fr, int cl0_, int acol0, LAS float* CW, LAS float* BD, LAS float* RSL) const {
;     ...
;                         const int cl = bj * 128 + cl0 + 4 * n, gcol = bj * DFF + acol0 + cl0 + 4 * n; const f32x4 x = acc[ai][bj][m][n] * rs;
;                         f32x4 s1, s2;
; #pragma unroll
;                         for (int i = 0; i < 4; ++i) { s1[i] = dpp_ror1(x[i]); s2[i] = dpp_ror2(x[i]); }
;                         if (SAMPLE) { const int t = fro & 3; const float* sp = state_conv + (size_t)((row - MP) >> 2) * 2 * UPW + gcol;
;                             const f32x4 S0 = *(const GAS f32x4*)sp, S1 = *(const GAS f32x4*)(sp + UPW);
; #pragma unroll
;                             for (int i = 0; i < 4; ++i) { s1[i] = (t >= 1) ? s1[i] : S1[i]; s2[i] = (t >= 2) ? s2[i] : (t == 1 ? S1[i] : S0[i]); }
;                             if (t >= 2) *(GAS f32x4*)(out + O_CVS + ((size_t)((row - MP) >> 2) * 2 + (t - 2)) * UPW + gcol) = x;
;                         } else if (m > 0) { const f32x4 xp = acc[ai][bj][m > 0 ? m - 1 : 0][n] * RSL[rl - 16];
; #pragma unroll
;                             for (int i = 0; i < 4; ++i) { s1[i] = dpp_ror1(fro == 15 ? xp[i] : x[i]); s2[i] = dpp_ror2(fro >= 14 ? xp[i] : x[i]); }
;                         } else { const int pb = (wr == 1) ? ai * 2 : 1;
;                             const int pr0 = (pb >> 1) * 128 + (pb & 1) * 64 + 62;
;                             const f32x4 b2 = *(const LAS f32x4*)(BD + (pb * 2 + 0) * 256 + cl) * RSL[pr0], b1 = *(const LAS f32x4*)(BD + (pb * 2 + 1) * 256 + cl) * RSL[pr0 + 1];
; #pragma unroll
;                             for (int i = 0; i < 4; ++i) { s1[i] = (fro >= 1) ? s1[i] : b1[i]; s2[i] = (fro >= 2) ? s2[i] : (fro == 1 ? b1[i] : b2[i]); }
;                         }
;                         const f32x4 w0 = *(const LAS f32x4*)(CW + cl), w1 = *(const LAS f32x4*)(CW + 256 + cl), w2 = *(const LAS f32x4*)(CW + 512 + cl), cb = *(const LAS f32x4*)(CW + 768 + cl);
;                         cv2[bj] = cb + s2 * w0 + s1 * w1 + x * w2;
;                         if (!SAMPLE && ai == 0 && m == 0) { if (rl < 2) { v2u w; w.x = cvt_pk_bf16(x[0], x[1]); w.y = cvt_pk_bf16(x[2], x[3]); *(GAS v2u*)(UPF + ((size_t)u.pm * 2 + rl) * UPW + gcol) = w; } }
	v_pk_mul_f32 v[134:135], v[26:27], v[138:139] op_sel_hi:[1,0]
	v_pk_mul_f32 v[136:137], v[28:29], v[138:139] op_sel_hi:[1,0]
	v_pk_mul_f32 v[150:151], v[42:43], v[168:169] op_sel_hi:[1,0]
	v_pk_mul_f32 v[152:153], v[44:45], v[168:169] op_sel_hi:[1,0]
	v_cndmask_b32_e64 v154, v134, v150, s[4:5]
	v_cndmask_b32_e64 v155, v135, v151, s[4:5]
	v_cndmask_b32_e64 v156, v136, v152, s[4:5]
	v_cndmask_b32_e64 v157, v137, v153, s[4:5]
	v_cndmask_b32_e64 v150, v134, v150, s[2:3]
	v_cndmask_b32_e64 v151, v135, v151, s[2:3]
	v_cndmask_b32_e64 v152, v136, v152, s[2:3]
	v_cndmask_b32_e64 v153, v137, v153, s[2:3]
	v_fmac_f32_dpp v240, v150, v228 row_ror:2 row_mask:0xf bank_mask:0xf
	v_fmac_f32_dpp v241, v151, v229 row_ror:2 row_mask:0xf bank_mask:0xf
	v_fmac_f32_dpp v242, v152, v230 row_ror:2 row_mask:0xf bank_mask:0xf
	v_fmac_f32_dpp v243, v153, v231 row_ror:2 row_mask:0xf bank_mask:0xf
	v_fmac_f32_dpp v240, v154, v232 row_ror:1 row_mask:0xf bank_mask:0xf
	v_fmac_f32_dpp v241, v155, v233 row_ror:1 row_mask:0xf bank_mask:0xf
	v_fmac_f32_dpp v242, v156, v234 row_ror:1 row_mask:0xf bank_mask:0xf
	v_fmac_f32_dpp v243, v157, v235 row_ror:1 row_mask:0xf bank_mask:0xf
	v_pk_fma_f32 v[164:165], v[134:135], v[236:237], v[240:241]
	v_pk_fma_f32 v[166:167], v[136:137], v[238:239], v[242:243]
	v_pk_mul_f32 v[134:135], v[160:161], v[160:161]
	v_pk_mul_f32 v[136:137], v[162:163], v[162:163]
	v_pk_fma_f32 v[134:135], v[134:135], s[54:55], 1.0 op_sel_hi:[1,0,0]
	v_pk_mul_f32 v[150:151], v[160:161], s[56:57] op_sel_hi:[1,0]
	v_pk_fma_f32 v[136:137], v[136:137], s[54:55], 1.0 op_sel_hi:[1,0,0]
	v_pk_mul_f32 v[152:153], v[162:163], s[56:57] op_sel_hi:[1,0]
	v_pk_mul_f32 v[134:135], v[150:151], v[134:135]
	v_pk_mul_f32 v[136:137], v[152:153], v[136:137]
	v_pk_mul_f32 v[134:135], v[134:135], s[58:59] op_sel_hi:[1,0]
	v_pk_mul_f32 v[136:137], v[136:137], s[58:59] op_sel_hi:[1,0]
	v_exp_f32_e32 v134, v134
	v_exp_f32_e32 v135, v135
	v_exp_f32_e32 v136, v136
	v_exp_f32_e32 v137, v137
	v_pk_add_f32 v[134:135], v[134:135], 1.0 op_sel_hi:[1,0]
	s_nop 0
	v_pk_add_f32 v[136:137], v[136:137], 1.0 op_sel_hi:[1,0]
	v_rcp_f32_e32 v134, v134
	v_rcp_f32_e32 v135, v135
	v_rcp_f32_e32 v136, v136
	v_rcp_f32_e32 v137, v137
	v_pk_mul_f32 v[134:135], v[160:161], v[134:135]
	v_pk_mul_f32 v[136:137], v[162:163], v[136:137]
	v_pk_mul_f32 v[134:135], v[164:165], v[134:135]
	v_pk_mul_f32 v[136:137], v[166:167], v[136:137]
	s_nop 0
	v_cvt_pk_bf16_f32 v130, v134, v135
	v_cvt_pk_bf16_f32 v131, v136, v137
	s_waitcnt lgkmcnt(4)
	v_pk_mul_f32 v[134:135], v[22:23], v[138:139] op_sel_hi:[1,0]
	v_pk_mul_f32 v[136:137], v[24:25], v[138:139] op_sel_hi:[1,0]
	v_pk_mul_f32 v[150:151], v[38:39], v[168:169] op_sel_hi:[1,0]
	v_pk_mul_f32 v[152:153], v[40:41], v[168:169] op_sel_hi:[1,0]
	v_cndmask_b32_e64 v154, v134, v150, s[4:5]
	v_cndmask_b32_e64 v155, v135, v151, s[4:5]
	v_cndmask_b32_e64 v156, v136, v152, s[4:5]
	v_cndmask_b32_e64 v157, v137, v153, s[4:5]
	v_cndmask_b32_e64 v150, v134, v150, s[2:3]
	v_cndmask_b32_e64 v151, v135, v151, s[2:3]
	v_cndmask_b32_e64 v152, v136, v152, s[2:3]
	v_cndmask_b32_e64 v153, v137, v153, s[2:3]
	v_fmac_f32_dpp v146, v150, v244 row_ror:2 row_mask:0xf bank_mask:0xf
	v_fmac_f32_dpp v147, v151, v245 row_ror:2 row_mask:0xf bank_mask:0xf
	v_fmac_f32_dpp v148, v152, v246 row_ror:2 row_mask:0xf bank_mask:0xf
	v_fmac_f32_dpp v149, v153, v247 row_ror:2 row_mask:0xf bank_mask:0xf
	v_fmac_f32_dpp v146, v154, v248 row_ror:1 row_mask:0xf bank_mask:0xf
	v_fmac_f32_dpp v147, v155, v249 row_ror:1 row_mask:0xf bank_mask:0xf
	v_fmac_f32_dpp v148, v156, v250 row_ror:1 row_mask:0xf bank_mask:0xf
	v_fmac_f32_dpp v149, v157, v251 row_ror:1 row_mask:0xf bank_mask:0xf
	v_pk_fma_f32 v[160:161], v[134:135], v[142:143], v[146:147]
	v_pk_fma_f32 v[162:163], v[136:137], v[144:145], v[148:149]
	s_waitcnt lgkmcnt(0)
	v_pk_mul_f32 v[134:135], v[18:19], v[138:139] op_sel_hi:[1,0]
	v_pk_mul_f32 v[136:137], v[20:21], v[138:139] op_sel_hi:[1,0]
	v_pk_mul_f32 v[150:151], v[34:35], v[168:169] op_sel_hi:[1,0]
	v_pk_mul_f32 v[152:153], v[36:37], v[168:169] op_sel_hi:[1,0]
	v_cndmask_b32_e64 v154, v134, v150, s[4:5]
	v_cndmask_b32_e64 v155, v135, v151, s[4:5]
	v_cndmask_b32_e64 v156, v136, v152, s[4:5]
	v_cndmask_b32_e64 v157, v137, v153, s[4:5]
	v_cndmask_b32_e64 v150, v134, v150, s[2:3]
	v_cndmask_b32_e64 v151, v135, v151, s[2:3]
	v_cndmask_b32_e64 v152, v136, v152, s[2:3]
	v_cndmask_b32_e64 v153, v137, v153, s[2:3]
	v_fmac_f32_dpp v216, v150, v204 row_ror:2 row_mask:0xf bank_mask:0xf
	v_fmac_f32_dpp v217, v151, v205 row_ror:2 row_mask:0xf bank_mask:0xf
	v_fmac_f32_dpp v218, v152, v206 row_ror:2 row_mask:0xf bank_mask:0xf
	v_fmac_f32_dpp v219, v153, v207 row_ror:2 row_mask:0xf bank_mask:0xf
	v_fmac_f32_dpp v216, v154, v208 row_ror:1 row_mask:0xf bank_mask:0xf
	v_fmac_f32_dpp v217, v155, v209 row_ror:1 row_mask:0xf bank_mask:0xf
	v_fmac_f32_dpp v218, v156, v210 row_ror:1 row_mask:0xf bank_mask:0xf
	v_fmac_f32_dpp v219, v157, v211 row_ror:1 row_mask:0xf bank_mask:0xf
	v_pk_fma_f32 v[164:165], v[134:135], v[212:213], v[216:217]
	v_pk_fma_f32 v[166:167], v[136:137], v[214:215], v[218:219]
	v_pk_mul_f32 v[134:135], v[160:161], v[160:161]
	v_pk_mul_f32 v[136:137], v[162:163], v[162:163]
	v_pk_fma_f32 v[134:135], v[134:135], s[54:55], 1.0 op_sel_hi:[1,0,0]
	v_pk_mul_f32 v[150:151], v[160:161], s[56:57] op_sel_hi:[1,0]
	v_pk_fma_f32 v[136:137], v[136:137], s[54:55], 1.0 op_sel_hi:[1,0,0]
	v_pk_mul_f32 v[152:153], v[162:163], s[56:57] op_sel_hi:[1,0]
	v_pk_mul_f32 v[134:135], v[150:151], v[134:135]
	v_pk_mul_f32 v[136:137], v[152:153], v[136:137]
	v_pk_mul_f32 v[134:135], v[134:135], s[58:59] op_sel_hi:[1,0]
	v_pk_mul_f32 v[136:137], v[136:137], s[58:59] op_sel_hi:[1,0]
	v_exp_f32_e32 v134, v134
	v_exp_f32_e32 v135, v135
	v_exp_f32_e32 v136, v136
	v_exp_f32_e32 v137, v137
	v_pk_add_f32 v[134:135], v[134:135], 1.0 op_sel_hi:[1,0]
	s_nop 0
	v_pk_add_f32 v[136:137], v[136:137], 1.0 op_sel_hi:[1,0]
	v_rcp_f32_e32 v134, v134
	v_rcp_f32_e32 v135, v135
	v_rcp_f32_e32 v136, v136
	v_rcp_f32_e32 v137, v137
	v_pk_mul_f32 v[134:135], v[160:161], v[134:135]
	v_pk_mul_f32 v[136:137], v[162:163], v[136:137]
	v_pk_mul_f32 v[134:135], v[164:165], v[134:135]
	v_pk_mul_f32 v[136:137], v[166:167], v[136:137]
	s_nop 0
	v_cvt_pk_bf16_f32 v132, v134, v135
	v_cvt_pk_bf16_f32 v133, v136, v137
	s_and_saveexec_b64 s[0:1], vcc
	s_cbranch_execz .LBB0_2618
	v_add_u32_e32 v136, s16, v158
	v_mov_b64_e32 v[134:135], s[50:51]
	v_mad_i64_i32 v[134:135], s[2:3], v136, s82, v[134:135]
	v_ashrrev_i32_e32 v141, 31, v140
	v_lshl_add_u64 v[134:135], s[36:37], 1, v[134:135]
	v_lshl_add_u64 v[134:135], v[140:141], 1, v[134:135]
	global_store_dwordx4 v[134:135], v[130:133], off
